# attention fast path: exp and row sums first, overflow guard on the row sums (redo through exact rescale path if tripped), m_ref kept in place, 2-pair mask
# baseline (speedup 1.0000x reference)
.LBB0_815:
	s_mov_b32 s24, 0
	s_mul_i32 s14, s10, 0x8a00
	s_cmp_eq_u32 s9, 0
	s_mov_b32 s13, 0
	s_cselect_b64 s[36:37], -1, 0
	v_add_u32_e32 v188, s14, v186
	v_add_u32_e32 v189, s14, v187

.Latt_domask0:
	v_add_u32_e32 v164, s13, v183
	v_sub_u32_e32 v165, v162, v164
	s_bitcmp1_b32 s13, 5
	s_cbranch_scc1 .Latt_m0b
	v_cmp_lt_i32_e64 s[20:21], 0, v165
	v_cmp_lt_i32_e64 s[22:23], 1, v165
	s_nop 0
	v_cndmask_b32_e64 v80, v80, v205, s[20:21]
	v_cmp_lt_i32_e64 s[20:21], 2, v165
	v_cndmask_b32_e64 v81, v81, v205, s[22:23]
	v_cmp_lt_i32_e64 s[22:23], 3, v165
	v_cndmask_b32_e64 v82, v82, v205, s[20:21]
	v_cmp_lt_i32_e64 s[20:21], 8, v165
	v_cndmask_b32_e64 v83, v83, v205, s[22:23]
	v_cmp_lt_i32_e64 s[22:23], 9, v165
	v_cndmask_b32_e64 v84, v84, v205, s[20:21]
	v_cmp_lt_i32_e64 s[20:21], 10, v165
	v_cndmask_b32_e64 v85, v85, v205, s[22:23]
	v_cmp_lt_i32_e64 s[22:23], 11, v165
	v_cndmask_b32_e64 v86, v86, v205, s[20:21]
	v_cmp_lt_i32_e64 s[20:21], 16, v165
	v_cndmask_b32_e64 v87, v87, v205, s[22:23]
	v_cmp_lt_i32_e64 s[22:23], 17, v165
	v_cndmask_b32_e64 v88, v88, v205, s[20:21]
	v_cmp_lt_i32_e64 s[20:21], 18, v165
	v_cndmask_b32_e64 v89, v89, v205, s[22:23]
	v_cmp_lt_i32_e64 s[22:23], 19, v165
	v_cndmask_b32_e64 v90, v90, v205, s[20:21]
	v_cmp_lt_i32_e64 s[20:21], 24, v165
	v_cndmask_b32_e64 v91, v91, v205, s[22:23]
	v_cmp_lt_i32_e64 s[22:23], 25, v165
	v_cndmask_b32_e64 v92, v92, v205, s[20:21]
	v_cmp_lt_i32_e64 s[20:21], 26, v165
	v_cndmask_b32_e64 v93, v93, v205, s[22:23]
	v_cmp_lt_i32_e64 s[22:23], 27, v165
	v_cndmask_b32_e64 v94, v94, v205, s[20:21]
	s_nop 0
	v_cndmask_b32_e64 v95, v95, v205, s[22:23]
	v_mov_b32_e32 v64, v205
	v_mov_b32_e32 v65, v205
	v_mov_b32_e32 v66, v205
	v_mov_b32_e32 v67, v205
	v_mov_b32_e32 v68, v205
	v_mov_b32_e32 v69, v205
	v_mov_b32_e32 v70, v205
	v_mov_b32_e32 v71, v205
	v_mov_b32_e32 v72, v205
	v_mov_b32_e32 v73, v205
	v_mov_b32_e32 v74, v205
	v_mov_b32_e32 v75, v205
	v_mov_b32_e32 v76, v205
	v_mov_b32_e32 v77, v205
	v_mov_b32_e32 v78, v205
	v_mov_b32_e32 v79, v205
	s_branch .LBB0_822
.Latt_m0b:
	v_add_u32_e32 v166, 32, v165
	s_nop 0
	v_cmp_lt_i32_e64 s[20:21], 0, v166
	v_cmp_lt_i32_e64 s[22:23], 1, v166
	s_nop 0
	v_cndmask_b32_e64 v64, v64, v205, s[20:21]
	v_cmp_lt_i32_e64 s[20:21], 2, v166
	v_cndmask_b32_e64 v65, v65, v205, s[22:23]
	v_cmp_lt_i32_e64 s[22:23], 3, v166
	v_cndmask_b32_e64 v66, v66, v205, s[20:21]
	v_cmp_lt_i32_e64 s[20:21], 8, v166
	v_cndmask_b32_e64 v67, v67, v205, s[22:23]
	v_cmp_lt_i32_e64 s[22:23], 9, v166
	v_cndmask_b32_e64 v68, v68, v205, s[20:21]
	v_cmp_lt_i32_e64 s[20:21], 10, v166
	v_cndmask_b32_e64 v69, v69, v205, s[22:23]
	v_cmp_lt_i32_e64 s[22:23], 11, v166
	v_cndmask_b32_e64 v70, v70, v205, s[20:21]
	v_cmp_lt_i32_e64 s[20:21], 16, v166
	v_cndmask_b32_e64 v71, v71, v205, s[22:23]
	v_cmp_lt_i32_e64 s[22:23], 17, v166
	v_cndmask_b32_e64 v72, v72, v205, s[20:21]
	v_cmp_lt_i32_e64 s[20:21], 18, v166
	v_cndmask_b32_e64 v73, v73, v205, s[22:23]
	v_cmp_lt_i32_e64 s[22:23], 19, v166
	v_cndmask_b32_e64 v74, v74, v205, s[20:21]
	v_cmp_lt_i32_e64 s[20:21], 24, v166
	v_cndmask_b32_e64 v75, v75, v205, s[22:23]
	v_cmp_lt_i32_e64 s[22:23], 25, v166
	v_cndmask_b32_e64 v76, v76, v205, s[20:21]
	v_cmp_lt_i32_e64 s[20:21], 26, v166
	v_cndmask_b32_e64 v77, v77, v205, s[22:23]
	v_cmp_lt_i32_e64 s[22:23], 27, v166
	v_cndmask_b32_e64 v78, v78, v205, s[20:21]
	s_nop 0
	v_cndmask_b32_e64 v79, v79, v205, s[22:23]
	s_branch .LBB0_822

.Latt_domask2:
	v_add_u32_e32 v164, s13, v183
	v_sub_u32_e32 v165, v162, v164
	s_bitcmp1_b32 s13, 5
	s_cbranch_scc1 .Latt_m2b
	v_cmp_gt_i32_e64 s[20:21], 0, v165
	v_cmp_gt_i32_e64 s[22:23], 1, v165
	s_nop 0
	v_cndmask_b32_e64 v80, v80, v205, s[20:21]
	v_cmp_gt_i32_e64 s[20:21], 2, v165
	v_cndmask_b32_e64 v81, v81, v205, s[22:23]
	v_cmp_gt_i32_e64 s[22:23], 3, v165
	v_cndmask_b32_e64 v82, v82, v205, s[20:21]
	v_cmp_gt_i32_e64 s[20:21], 8, v165
	v_cndmask_b32_e64 v83, v83, v205, s[22:23]
	v_cmp_gt_i32_e64 s[22:23], 9, v165
	v_cndmask_b32_e64 v84, v84, v205, s[20:21]
	v_cmp_gt_i32_e64 s[20:21], 10, v165
	v_cndmask_b32_e64 v85, v85, v205, s[22:23]
	v_cmp_gt_i32_e64 s[22:23], 11, v165
	v_cndmask_b32_e64 v86, v86, v205, s[20:21]
	v_cmp_gt_i32_e64 s[20:21], 16, v165
	v_cndmask_b32_e64 v87, v87, v205, s[22:23]
	v_cmp_gt_i32_e64 s[22:23], 17, v165
	v_cndmask_b32_e64 v88, v88, v205, s[20:21]
	v_cmp_gt_i32_e64 s[20:21], 18, v165
	v_cndmask_b32_e64 v89, v89, v205, s[22:23]
	v_cmp_gt_i32_e64 s[22:23], 19, v165
	v_cndmask_b32_e64 v90, v90, v205, s[20:21]
	v_cmp_gt_i32_e64 s[20:21], 24, v165
	v_cndmask_b32_e64 v91, v91, v205, s[22:23]
	v_cmp_gt_i32_e64 s[22:23], 25, v165
	v_cndmask_b32_e64 v92, v92, v205, s[20:21]
	v_cmp_gt_i32_e64 s[20:21], 26, v165
	v_cndmask_b32_e64 v93, v93, v205, s[22:23]
	v_cmp_gt_i32_e64 s[22:23], 27, v165
	v_cndmask_b32_e64 v94, v94, v205, s[20:21]
	s_nop 0
	v_cndmask_b32_e64 v95, v95, v205, s[22:23]
	s_branch .LBB0_822
.Latt_m2b:
	v_add_u32_e32 v166, 32, v165
	v_mov_b32_e32 v80, v205
	v_mov_b32_e32 v81, v205
	v_mov_b32_e32 v82, v205
	v_mov_b32_e32 v83, v205
	v_mov_b32_e32 v84, v205
	v_mov_b32_e32 v85, v205
	v_mov_b32_e32 v86, v205
	v_mov_b32_e32 v87, v205
	v_mov_b32_e32 v88, v205
	v_mov_b32_e32 v89, v205
	v_mov_b32_e32 v90, v205
	v_mov_b32_e32 v91, v205
	v_mov_b32_e32 v92, v205
	v_mov_b32_e32 v93, v205
	v_mov_b32_e32 v94, v205
	v_mov_b32_e32 v95, v205
	v_cmp_gt_i32_e64 s[20:21], 0, v166
	v_cmp_gt_i32_e64 s[22:23], 1, v166
	s_nop 0
	v_cndmask_b32_e64 v64, v64, v205, s[20:21]
	v_cmp_gt_i32_e64 s[20:21], 2, v166
	v_cndmask_b32_e64 v65, v65, v205, s[22:23]
	v_cmp_gt_i32_e64 s[22:23], 3, v166
	v_cndmask_b32_e64 v66, v66, v205, s[20:21]
	v_cmp_gt_i32_e64 s[20:21], 8, v166
	v_cndmask_b32_e64 v67, v67, v205, s[22:23]
	v_cmp_gt_i32_e64 s[22:23], 9, v166
	v_cndmask_b32_e64 v68, v68, v205, s[20:21]
	v_cmp_gt_i32_e64 s[20:21], 10, v166
	v_cndmask_b32_e64 v69, v69, v205, s[22:23]
	v_cmp_gt_i32_e64 s[22:23], 11, v166
	v_cndmask_b32_e64 v70, v70, v205, s[20:21]
	v_cmp_gt_i32_e64 s[20:21], 16, v166
	v_cndmask_b32_e64 v71, v71, v205, s[22:23]
	v_cmp_gt_i32_e64 s[22:23], 17, v166
	v_cndmask_b32_e64 v72, v72, v205, s[20:21]
	v_cmp_gt_i32_e64 s[20:21], 18, v166
	v_cndmask_b32_e64 v73, v73, v205, s[22:23]
	v_cmp_gt_i32_e64 s[22:23], 19, v166
	v_cndmask_b32_e64 v74, v74, v205, s[20:21]
	v_cmp_gt_i32_e64 s[20:21], 24, v166
	v_cndmask_b32_e64 v75, v75, v205, s[22:23]
	v_cmp_gt_i32_e64 s[22:23], 25, v166
	v_cndmask_b32_e64 v76, v76, v205, s[20:21]
	v_cmp_gt_i32_e64 s[20:21], 26, v166
	v_cndmask_b32_e64 v77, v77, v205, s[22:23]
	v_cmp_gt_i32_e64 s[22:23], 27, v166
	v_cndmask_b32_e64 v78, v78, v205, s[20:21]
	s_nop 0
	v_cndmask_b32_e64 v79, v79, v205, s[22:23]
.LBB0_822:
	s_nop 2
	s_cmp_lg_u32 s24, 0
	s_cbranch_scc1 .Latt_slow
	ds_read2_b64 v[164:167], v188 offset1:2
	v_add_u32_e32 v201, 0x2000, v188
	ds_read2_b64 v[168:171], v201 offset0:32 offset1:34
	ds_read2_b64 v[172:175], v188 offset0:4 offset1:6
	ds_read2_b64 v[238:241], v201 offset0:36 offset1:38
	v_exp_f32_e32 v80, v80
	v_exp_f32_e32 v64, v64
	v_exp_f32_e32 v81, v81
	v_exp_f32_e32 v65, v65
	v_exp_f32_e32 v82, v82
	v_exp_f32_e32 v66, v66
	v_exp_f32_e32 v83, v83
	v_exp_f32_e32 v67, v67
	v_exp_f32_e32 v84, v84
	v_exp_f32_e32 v68, v68
	v_exp_f32_e32 v85, v85
	v_exp_f32_e32 v69, v69
	v_exp_f32_e32 v86, v86
	v_exp_f32_e32 v70, v70
	v_exp_f32_e32 v87, v87
	v_exp_f32_e32 v71, v71
	v_exp_f32_e32 v88, v88
	v_exp_f32_e32 v72, v72
	v_exp_f32_e32 v89, v89
	v_exp_f32_e32 v73, v73
	v_exp_f32_e32 v90, v90
	v_exp_f32_e32 v74, v74
	v_exp_f32_e32 v91, v91
	v_exp_f32_e32 v75, v75
	v_exp_f32_e32 v92, v92
	v_exp_f32_e32 v76, v76
	v_exp_f32_e32 v93, v93
	v_exp_f32_e32 v77, v77
	v_exp_f32_e32 v94, v94
	v_exp_f32_e32 v78, v78
	v_exp_f32_e32 v95, v95
	v_exp_f32_e32 v79, v79
	v_add_f32_e32 v197, v80, v81
	v_add_f32_e32 v198, v64, v65
	v_add_f32_e32 v197, v197, v82
	v_add_f32_e32 v198, v198, v66
	v_add_f32_e32 v197, v197, v83
	v_add_f32_e32 v198, v198, v67
	v_add_f32_e32 v197, v197, v84
	v_add_f32_e32 v198, v198, v68
	v_add_f32_e32 v197, v197, v85
	v_add_f32_e32 v198, v198, v69
	v_add_f32_e32 v197, v197, v86
	v_add_f32_e32 v198, v198, v70
	v_add_f32_e32 v197, v197, v87
	v_add_f32_e32 v198, v198, v71
	v_add_f32_e32 v197, v197, v88
	v_add_f32_e32 v198, v198, v72
	v_add_f32_e32 v197, v197, v89
	v_add_f32_e32 v198, v198, v73
	v_add_f32_e32 v197, v197, v90
	v_add_f32_e32 v198, v198, v74
	v_add_f32_e32 v197, v197, v91
	v_add_f32_e32 v198, v198, v75
	v_add_f32_e32 v197, v197, v92
	v_add_f32_e32 v198, v198, v76
	v_add_f32_e32 v197, v197, v93
	v_add_f32_e32 v198, v198, v77
	v_add_f32_e32 v197, v197, v94
	v_add_f32_e32 v198, v198, v78
	v_add_f32_e32 v197, v197, v95
	v_add_f32_e32 v198, v198, v79
	v_max_f32_e32 v199, v197, v198
	v_cmp_ngt_f32_e32 vcc, 0x5d800000, v199
	s_cbranch_vccnz .Latt_redo
	v_add_f32_e32 v149, v149, v197
	v_add_f32_e32 v148, v148, v198
	v_cvt_pk_bf16_f32 v80, v80, v81
	v_cvt_pk_bf16_f32 v81, v82, v83
	v_cvt_pk_bf16_f32 v82, v84, v85
	v_cvt_pk_bf16_f32 v83, v86, v87
	v_cvt_pk_bf16_f32 v84, v88, v89
	v_cvt_pk_bf16_f32 v85, v90, v91
	v_cvt_pk_bf16_f32 v86, v92, v93
	v_cvt_pk_bf16_f32 v87, v94, v95
	v_cvt_pk_bf16_f32 v64, v64, v65
	v_cvt_pk_bf16_f32 v65, v66, v67
	v_cvt_pk_bf16_f32 v66, v68, v69
	v_cvt_pk_bf16_f32 v67, v70, v71
	v_cvt_pk_bf16_f32 v68, v72, v73
	v_cvt_pk_bf16_f32 v69, v74, v75
	v_cvt_pk_bf16_f32 v70, v76, v77
	v_cvt_pk_bf16_f32 v71, v78, v79
	s_branch .Latt_pv
.Latt_redo:
	s_mov_b32 s24, 1
	s_branch .Latt_noskip
.Latt_slow:
	s_mov_b32 s24, 0
	v_mov_b32_e32 v199, v159
	v_mov_b32_e32 v200, v158
	v_mov_b32_e32 v159, 0
	v_mov_b32_e32 v158, 0
	v_max_f32_e32 v164, v81, v81
	v_max_f32_e32 v165, v80, v80
	v_max_f32_e32 v164, v165, v164
	v_max3_f32 v164, v164, v82, v83
	v_max3_f32 v164, v164, v84, v85
	v_max3_f32 v164, v164, v86, v87
	v_max3_f32 v164, v164, v88, v89
	v_max3_f32 v164, v164, v90, v91
	v_max3_f32 v164, v164, v92, v93
	v_max3_f32 v164, v164, v94, v95
	v_mov_b32_e32 v165, v164
	s_nop 1
	v_permlane32_swap_b32_e32 v164, v165
	v_max3_f32 v190, v159, v164, v165
	v_sub_f32_e32 v80, v80, v190
	v_sub_f32_e32 v81, v81, v190
	v_exp_f32_e32 v80, v80
	v_sub_f32_e32 v82, v82, v190
	v_exp_f32_e32 v81, v81
	v_sub_f32_e32 v83, v83, v190
	v_exp_f32_e32 v82, v82
	v_exp_f32_e32 v83, v83
	v_sub_f32_e32 v84, v84, v190
	v_sub_f32_e32 v164, v159, v190
	v_add_f32_e32 v159, 0, v80
	v_exp_f32_e32 v84, v84
	v_add_f32_e32 v159, v81, v159
	v_add_f32_e32 v159, v82, v159
	v_sub_f32_e32 v85, v85, v190
	v_add_f32_e32 v159, v83, v159
	v_exp_f32_e32 v85, v85
	v_add_f32_e32 v159, v84, v159
	v_cvt_pk_bf16_f32 v80, v80, v81
	v_cvt_pk_bf16_f32 v81, v82, v83
	v_cvt_pk_bf16_f32 v82, v84, v85
	v_max_f32_e32 v83, v65, v65
	v_max_f32_e32 v84, v64, v64
	v_max_f32_e32 v83, v84, v83
	v_max3_f32 v83, v83, v66, v67
	v_max3_f32 v83, v83, v68, v69
	v_max3_f32 v83, v83, v70, v71
	v_sub_f32_e32 v86, v86, v190
	v_max3_f32 v83, v83, v72, v73
	v_exp_f32_e32 v165, v86
	v_sub_f32_e32 v86, v87, v190
	v_max3_f32 v83, v83, v74, v75
	v_exp_f32_e32 v169, v86
	v_sub_f32_e32 v86, v88, v190
	v_max3_f32 v83, v83, v76, v77
	v_add_f32_e32 v193, v85, v159
	v_exp_f32_e32 v159, v86
	v_sub_f32_e32 v86, v89, v190
	v_max3_f32 v88, v83, v78, v79
	v_exp_f32_e32 v89, v86
	v_sub_f32_e32 v86, v90, v190
	v_mov_b32_e32 v90, v88
	v_exp_f32_e32 v167, v86
	v_sub_f32_e32 v86, v91, v190
	v_permlane32_swap_b32_e32 v88, v90
	v_exp_f32_e32 v91, v164
	v_exp_f32_e32 v171, v86
	v_max3_f32 v191, v158, v88, v90
	v_sub_f32_e32 v64, v64, v191
	v_exp_f32_e32 v194, v64
	v_sub_f32_e32 v64, v65, v191
	v_exp_f32_e32 v195, v64
	v_sub_f32_e32 v64, v66, v191
	v_exp_f32_e32 v196, v64
	v_sub_f32_e32 v64, v67, v191
	v_exp_f32_e32 v67, v64
	v_sub_f32_e32 v65, v68, v191
	v_add_f32_e32 v64, 0, v194
	v_exp_f32_e32 v68, v65
	v_sub_f32_e32 v65, v69, v191
	v_add_f32_e32 v64, v195, v64
	v_exp_f32_e32 v69, v65
	v_sub_f32_e32 v65, v70, v191
	v_add_f32_e32 v64, v196, v64
	v_exp_f32_e32 v164, v65
	v_sub_f32_e32 v65, v71, v191
	v_add_f32_e32 v64, v67, v64
	v_exp_f32_e32 v168, v65
	v_sub_f32_e32 v66, v72, v191
	v_sub_f32_e32 v90, v158, v191
	v_add_f32_e32 v64, v68, v64
	v_exp_f32_e32 v158, v66
	v_sub_f32_e32 v66, v73, v191
	v_add_f32_e32 v192, v69, v64
	v_exp_f32_e32 v88, v66
	v_sub_f32_e32 v66, v74, v191
	v_pk_add_f32 v[64:65], v[164:165], v[192:193]
	v_exp_f32_e32 v166, v66
	v_sub_f32_e32 v66, v75, v191
	v_sub_f32_e32 v86, v92, v190
	v_pk_add_f32 v[64:65], v[168:169], v[64:65]
	v_exp_f32_e32 v170, v66
	v_sub_f32_e32 v66, v76, v191
	v_exp_f32_e32 v173, v86
	v_sub_f32_e32 v86, v93, v190
	v_pk_add_f32 v[64:65], v[158:159], v[64:65]
	v_exp_f32_e32 v172, v66
	v_sub_f32_e32 v66, v77, v191
	v_exp_f32_e32 v93, v86
	v_sub_f32_e32 v86, v94, v190
	v_pk_add_f32 v[64:65], v[88:89], v[64:65]
	v_exp_f32_e32 v92, v66
	v_sub_f32_e32 v66, v78, v191
	v_exp_f32_e32 v175, v86
	v_sub_f32_e32 v86, v95, v190
	v_pk_add_f32 v[64:65], v[166:167], v[64:65]
	v_exp_f32_e32 v174, v66
	v_sub_f32_e32 v66, v79, v191
	v_exp_f32_e32 v95, v86
	v_pk_add_f32 v[64:65], v[170:171], v[64:65]
	v_exp_f32_e32 v94, v66
	v_pk_add_f32 v[64:65], v[172:173], v[64:65]
	v_exp_f32_e32 v90, v90
	v_pk_add_f32 v[64:65], v[92:93], v[64:65]
	v_mov_b32_e32 v66, v91
	v_pk_add_f32 v[64:65], v[174:175], v[64:65]
	v_cvt_pk_bf16_f32 v83, v165, v169
	v_cvt_pk_bf16_f32 v84, v159, v89
	v_cvt_pk_bf16_f32 v85, v167, v171
	v_cvt_pk_bf16_f32 v86, v173, v93
	v_cvt_pk_bf16_f32 v87, v175, v95
	s_nop 0
	v_pk_add_f32 v[64:65], v[94:95], v[64:65]
	v_pk_mul_f32 v[46:47], v[46:47], v[66:67] op_sel_hi:[1,0]
	v_pk_mul_f32 v[44:45], v[44:45], v[66:67] op_sel_hi:[1,0]
	v_pk_mul_f32 v[42:43], v[42:43], v[66:67] op_sel_hi:[1,0]
	v_pk_mul_f32 v[40:41], v[40:41], v[66:67] op_sel_hi:[1,0]
	v_pk_mul_f32 v[38:39], v[38:39], v[66:67] op_sel_hi:[1,0]
	v_pk_mul_f32 v[36:37], v[36:37], v[66:67] op_sel_hi:[1,0]
	v_pk_mul_f32 v[34:35], v[34:35], v[66:67] op_sel_hi:[1,0]
	v_pk_mul_f32 v[32:33], v[32:33], v[66:67] op_sel_hi:[1,0]
	v_pk_mul_f32 v[62:63], v[62:63], v[66:67] op_sel_hi:[1,0]
	v_pk_mul_f32 v[60:61], v[60:61], v[66:67] op_sel_hi:[1,0]
	v_pk_mul_f32 v[58:59], v[58:59], v[66:67] op_sel_hi:[1,0]
	v_pk_mul_f32 v[56:57], v[56:57], v[66:67] op_sel_hi:[1,0]
	v_pk_mul_f32 v[54:55], v[54:55], v[66:67] op_sel_hi:[1,0]
	v_pk_mul_f32 v[52:53], v[52:53], v[66:67] op_sel_hi:[1,0]
	v_pk_mul_f32 v[50:51], v[50:51], v[66:67] op_sel_hi:[1,0]
	v_pk_mul_f32 v[48:49], v[48:49], v[66:67] op_sel_hi:[1,0]
	v_pk_fma_f32 v[148:149], v[148:149], v[90:91], v[64:65]
	v_cvt_pk_bf16_f32 v64, v194, v195
	v_cvt_pk_bf16_f32 v65, v196, v67
	v_cvt_pk_bf16_f32 v66, v68, v69
	v_cvt_pk_bf16_f32 v67, v164, v168
	v_cvt_pk_bf16_f32 v68, v158, v88
	v_cvt_pk_bf16_f32 v69, v166, v170
	v_cvt_pk_bf16_f32 v70, v172, v92
	v_cvt_pk_bf16_f32 v71, v174, v94
	ds_read2_b64 v[164:167], v188 offset1:2
	v_add_u32_e32 v201, 0x2000, v188
	ds_read2_b64 v[168:171], v201 offset0:32 offset1:34
	ds_read2_b64 v[172:175], v188 offset0:4 offset1:6
	ds_read2_b64 v[238:241], v201 offset0:36 offset1:38
	v_pk_mul_f32 v[30:31], v[30:31], v[90:91] op_sel_hi:[1,0]
	v_pk_mul_f32 v[28:29], v[28:29], v[90:91] op_sel_hi:[1,0]
	v_pk_mul_f32 v[26:27], v[26:27], v[90:91] op_sel_hi:[1,0]
	v_pk_mul_f32 v[24:25], v[24:25], v[90:91] op_sel_hi:[1,0]
	v_pk_mul_f32 v[22:23], v[22:23], v[90:91] op_sel_hi:[1,0]
	v_pk_mul_f32 v[20:21], v[20:21], v[90:91] op_sel_hi:[1,0]
	v_pk_mul_f32 v[18:19], v[18:19], v[90:91] op_sel_hi:[1,0]
	v_pk_mul_f32 v[16:17], v[16:17], v[90:91] op_sel_hi:[1,0]
	v_pk_mul_f32 v[14:15], v[14:15], v[90:91] op_sel_hi:[1,0]
	v_pk_mul_f32 v[12:13], v[12:13], v[90:91] op_sel_hi:[1,0]
	v_pk_mul_f32 v[10:11], v[10:11], v[90:91] op_sel_hi:[1,0]
	v_pk_mul_f32 v[8:9], v[8:9], v[90:91] op_sel_hi:[1,0]
	v_pk_mul_f32 v[6:7], v[6:7], v[90:91] op_sel_hi:[1,0]
	v_pk_mul_f32 v[4:5], v[4:5], v[90:91] op_sel_hi:[1,0]
	v_pk_mul_f32 v[2:3], v[2:3], v[90:91] op_sel_hi:[1,0]
	v_pk_mul_f32 v[0:1], v[0:1], v[90:91] op_sel_hi:[1,0]
	v_add_f32_e32 v190, v190, v199
	v_add_f32_e32 v191, v191, v200
	v_mul_f32_e32 v206, -1.0, v190
	v_mul_f32_e32 v222, -1.0, v191
	v_mov_b32_e32 v207, v206
	v_mov_b32_e32 v223, v222
	v_mov_b32_e32 v208, v206
	v_mov_b32_e32 v224, v222
	v_mov_b32_e32 v209, v206
	v_mov_b32_e32 v225, v222
	v_mov_b32_e32 v210, v206
	v_mov_b32_e32 v226, v222
	v_mov_b32_e32 v211, v206
	v_mov_b32_e32 v227, v222
	v_mov_b32_e32 v212, v206
	v_mov_b32_e32 v228, v222
	v_mov_b32_e32 v213, v206
	v_mov_b32_e32 v229, v222
	v_mov_b32_e32 v214, v206
	v_mov_b32_e32 v230, v222
	v_mov_b32_e32 v215, v206
	v_mov_b32_e32 v231, v222
	v_mov_b32_e32 v216, v206
	v_mov_b32_e32 v232, v222
	v_mov_b32_e32 v217, v206
	v_mov_b32_e32 v233, v222
	v_mov_b32_e32 v218, v206
	v_mov_b32_e32 v234, v222
	v_mov_b32_e32 v219, v206
	v_mov_b32_e32 v235, v222
	v_mov_b32_e32 v220, v206
	v_mov_b32_e32 v236, v222
	v_mov_b32_e32 v221, v206
	v_mov_b32_e32 v237, v222
	v_mov_b32_e32 v159, v190
	v_mov_b32_e32 v158, v191

.Latt_skipkt:
.Latt_tail:
	s_add_i32 s13, s13, 32
	v_add_u32_e32 v188, 64, v188
	s_cmpk_eq_i32 s13, 0x80
	v_add_u32_e32 v189, 0x1200, v189
	s_cbranch_scc1 .LBB0_824
	s_branch .LBB0_816

.LBB0_826:
	s_andn2_b64 vcc, exec, s[42:43]
	s_waitcnt lgkmcnt(0)
	s_barrier
	s_cbranch_vccz .LBB0_795
	s_mov_b32 s9, s12
	s_branch .LBB0_813
